# seam barriers: the early-acquire L1 invalidate is issued right behind the arrival atomic instead of after its acknowledgement
# baseline (speedup 1.0000x reference)
.LBB0_550:
	s_or_b64 exec, exec, s[4:5]
	s_waitcnt lgkmcnt(0)
	v_add_u32_e32 v0, 1, v0
	v_readlane_b32 s2, v252, 40
	v_readlane_b32 s6, v252, 38
	s_mov_b32 s4, 0x400001
	v_mul_lo_u32 v1, v0, s2
	v_readlane_b32 s7, v252, 39
	s_nop 0
	buffer_inv sc1
	s_branch .LBB0_552

.LBB0_567:
	s_or_b64 exec, exec, s[2:3]
	v_readlane_b32 s6, v252, 38
	s_mov_b32 s4, 0x400001
	v_readlane_b32 s7, v252, 39
	s_nop 0
	buffer_inv sc1
	s_branch .LBB0_569
